# in-projection epilogue: packed f16 results restaged in place through the LDS C tile and stored with row-contiguous 16-byte chunks (coalesced stores)
# speedup vs baseline: 1.0461x; 1.0221x over previous
; DI unsigned pack2(float a, float b) { f32x2 v = {a, b}; bfx2 r = __builtin_convertvector(v, bfx2); return __builtin_bit_cast(unsigned, r); }
; DI float sigmoidf_(float x) { return 1.f / (1.f + __expf(-x)); }
; template <int MODE, bool BIG = false> DI void gemm_tile(const Params& p, int tm, int tn, int kv, char* smem) {
;     ...
; #pragma unroll
;     for (int c8 = 0; c8 < 8; ++c8) {
;       float4 v0 = crow4[2 * c8], v1 = crow4[2 * c8 + 1];
;       float v[8] = {v0.x, v0.y, v0.z, v0.w, v1.x, v1.y, v1.z, v1.w};
;       if (g) {
; #pragma unroll
;         for (int e = 0; e < 8; ++e) v[e] = v[e] * sc * g[c8 * 8 + e];
;       } else if (region == 48) {
; #pragma unroll
;         for (int e = 0; e < 8; ++e) { int c = c8 * 8 + e; v[e] = c < 24 ? sigmoidf_(v[e] + p.gate_b[c]) : 0.f; }
;       }
;       *(uint4*)(proj + prow(m) + col0 + c8 * 8) = make_uint4(pack2(v[0], v[1]), pack2(v[2], v[3]), pack2(v[4], v[5]), pack2(v[6], v[7]));
;     }
.LBB0_124:
	s_or_b64 exec, exec, s[0:1]
	s_waitcnt lgkmcnt(1)
	v_cvt_pk_f16_f32 v128, v136, v137
	v_cvt_pk_f16_f32 v129, v138, v139
	s_waitcnt lgkmcnt(0)
	v_cvt_pk_f16_f32 v130, v132, v133
	v_cvt_pk_f16_f32 v131, v134, v135
	s_mov_b32 s38, 1
	s_andn2_b64 vcc, exec, s[20:21]
	s_mov_b64 s[0:1], 0
	ds_write_b128 v159, v[128:131] offset:112
	s_waitcnt lgkmcnt(0)
	s_barrier
	v_lshrrev_b32_e32 v144, 4, v173
	v_lshrrev_b32_e32 v145, 1, v173
	v_sub_u32_e32 v144, v144, v145
	v_mul_lo_u32 v144, v144, s33
	v_and_b32_e32 v145, 1, v173
	v_lshlrev_b32_e32 v145, 7, v145
	v_sub_u32_e32 v144, v144, v145
	v_and_b32_e32 v145, 15, v173
	v_lshl_add_u32 v144, v145, 4, v144
	v_ashrrev_i32_e32 v145, 31, v144
	v_lshl_add_u64 v[146:147], v[156:157], 0, v[144:145]
	v_lshrrev_b32_e32 v150, 4, v173
	v_mul_u32_u24_e32 v150, 0x210, v150
	v_bfe_u32 v151, v173, 3, 1
	v_lshl_add_u32 v150, v151, 8, v150
	v_and_b32_e32 v151, 7, v173
	v_lshl_add_u32 v150, v151, 4, v150
	v_mov_b32_e32 v144, 0x19000
	v_mov_b32_e32 v145, 0
	ds_read_b128 v[128:131], v150
	ds_read_b128 v[132:135], v150 offset:8448
	ds_read_b128 v[136:139], v150 offset:16896
	ds_read_b128 v[140:143], v150 offset:25344
	s_waitcnt lgkmcnt(3)
	global_store_dwordx4 v[146:147], v[128:131], off
	v_lshl_add_u64 v[146:147], v[144:145], 0, v[146:147]
	ds_read_b128 v[128:131], v150 offset:33792
	s_waitcnt lgkmcnt(3)
	global_store_dwordx4 v[146:147], v[132:135], off
	v_lshl_add_u64 v[146:147], v[144:145], 0, v[146:147]
	ds_read_b128 v[132:135], v150 offset:42240
	s_waitcnt lgkmcnt(3)
	global_store_dwordx4 v[146:147], v[136:139], off
	v_lshl_add_u64 v[146:147], v[144:145], 0, v[146:147]
	ds_read_b128 v[136:139], v150 offset:50688
	s_waitcnt lgkmcnt(3)
	global_store_dwordx4 v[146:147], v[140:143], off
	v_lshl_add_u64 v[146:147], v[144:145], 0, v[146:147]
	ds_read_b128 v[140:143], v150 offset:59136
	s_waitcnt lgkmcnt(3)
	global_store_dwordx4 v[146:147], v[128:131], off
	v_lshl_add_u64 v[146:147], v[144:145], 0, v[146:147]
	s_waitcnt lgkmcnt(2)
	global_store_dwordx4 v[146:147], v[132:135], off
	v_lshl_add_u64 v[146:147], v[144:145], 0, v[146:147]
	s_waitcnt lgkmcnt(1)
	global_store_dwordx4 v[146:147], v[136:139], off
	v_lshl_add_u64 v[146:147], v[144:145], 0, v[146:147]
	s_waitcnt lgkmcnt(0)
	global_store_dwordx4 v[146:147], v[140:143], off
	v_lshl_add_u64 v[146:147], v[144:145], 0, v[146:147]
	s_cbranch_vccz .LBB0_119

; DI unsigned pack2(float a, float b) { f32x2 v = {a, b}; bfx2 r = __builtin_convertvector(v, bfx2); return __builtin_bit_cast(unsigned, r); }
; DI float sigmoidf_(float x) { return 1.f / (1.f + __expf(-x)); }
; template <int MODE, bool BIG = false> DI void gemm_tile(const Params& p, int tm, int tn, int kv, char* smem) {
;     ...
;     for (int c8 = 0; c8 < 8; ++c8) {
;       float4 v0 = crow4[2 * c8], v1 = crow4[2 * c8 + 1];
;       float v[8] = {v0.x, v0.y, v0.z, v0.w, v1.x, v1.y, v1.z, v1.w};
;       if (g) {
; #pragma unroll
;         for (int e = 0; e < 8; ++e) v[e] = v[e] * sc * g[c8 * 8 + e];
;       } else if (region == 48) {
; #pragma unroll
;         for (int e = 0; e < 8; ++e) { int c = c8 * 8 + e; v[e] = c < 24 ? sigmoidf_(v[e] + p.gate_b[c]) : 0.f; }
;       }
;       *(uint4*)(proj + prow(m) + col0 + c8 * 8) = make_uint4(pack2(v[0], v[1]), pack2(v[2], v[3]), pack2(v[4], v[5]), pack2(v[6], v[7]));
.LBB0_143:
	s_or_b64 exec, exec, s[22:23]
	v_lshl_add_u32 v136, s38, 7, v160
	v_ashrrev_i32_e32 v137, 31, v136
	v_lshlrev_b64 v[138:139], 11, v[136:137]
	v_and_b32_e32 v138, 0xff800000, v138
	v_lshl_add_u64 v[138:139], s[18:19], 0, v[138:139]
	v_mad_i64_i32 v[136:137], s[0:1], v136, s33, v[138:139]
	v_lshl_add_u64 v[156:157], v[148:149], 1, v[136:137]
	ds_read_b128 v[140:143], v159 offset:32
	ds_read_b128 v[136:139], v159 offset:48
	s_waitcnt lgkmcnt(3)
	v_cvt_pk_f16_f32 v132, v132, v133
	v_cvt_pk_f16_f32 v133, v134, v135
	s_waitcnt lgkmcnt(2)
	v_cvt_pk_f16_f32 v134, v128, v129
	v_cvt_pk_f16_f32 v135, v130, v131
	ds_write_b128 v159, v[132:135]
	s_and_saveexec_b64 s[0:1], s[10:11]
	s_xor_b64 s[0:1], exec, s[0:1]
	s_cbranch_execz .LBB0_145
	global_load_dwordx4 v[128:131], v[150:151], off offset:48
	global_load_dwordx4 v[132:135], v[150:151], off offset:32
	s_waitcnt lgkmcnt(1)
	v_pk_mul_f32 v[140:141], v[154:155], v[140:141] op_sel_hi:[0,1]
	s_waitcnt lgkmcnt(0)
	v_pk_mul_f32 v[136:137], v[154:155], v[136:137] op_sel_hi:[0,1]
	v_pk_mul_f32 v[142:143], v[154:155], v[142:143] op_sel_hi:[0,1]
	v_pk_mul_f32 v[138:139], v[154:155], v[138:139] op_sel_hi:[0,1]
	s_waitcnt vmcnt(1)
	v_pk_mul_f32 v[138:139], v[138:139], v[130:131]
	s_waitcnt vmcnt(0)
	v_pk_mul_f32 v[142:143], v[142:143], v[134:135]
	v_pk_mul_f32 v[136:137], v[136:137], v[128:129]
	v_pk_mul_f32 v[140:141], v[140:141], v[132:133]

; DI unsigned pack2(float a, float b) { f32x2 v = {a, b}; bfx2 r = __builtin_convertvector(v, bfx2); return __builtin_bit_cast(unsigned, r); }
; DI float sigmoidf_(float x) { return 1.f / (1.f + __expf(-x)); }
; template <int MODE, bool BIG = false> DI void gemm_tile(const Params& p, int tm, int tn, int kv, char* smem) {
;     ...
;     for (int c8 = 0; c8 < 8; ++c8) {
;       float4 v0 = crow4[2 * c8], v1 = crow4[2 * c8 + 1];
;       float v[8] = {v0.x, v0.y, v0.z, v0.w, v1.x, v1.y, v1.z, v1.w};
;       if (g) {
; #pragma unroll
;         for (int e = 0; e < 8; ++e) v[e] = v[e] * sc * g[c8 * 8 + e];
;       } else if (region == 48) {
; #pragma unroll
;         for (int e = 0; e < 8; ++e) { int c = c8 * 8 + e; v[e] = c < 24 ? sigmoidf_(v[e] + p.gate_b[c]) : 0.f; }
;       }
;       *(uint4*)(proj + prow(m) + col0 + c8 * 8) = make_uint4(pack2(v[0], v[1]), pack2(v[2], v[3]), pack2(v[4], v[5]), pack2(v[6], v[7]));
.LBB0_149:
	s_or_b64 exec, exec, s[22:23]
	ds_read_b128 v[132:135], v159 offset:64
	ds_read_b128 v[128:131], v159 offset:80
	s_waitcnt lgkmcnt(3)
	v_cvt_pk_f16_f32 v140, v140, v141
	v_cvt_pk_f16_f32 v141, v142, v143
	s_waitcnt lgkmcnt(2)
	v_cvt_pk_f16_f32 v142, v136, v137
	v_cvt_pk_f16_f32 v143, v138, v139
	ds_write_b128 v159, v[140:143] offset:16
	s_and_saveexec_b64 s[0:1], s[10:11]
	s_xor_b64 s[0:1], exec, s[0:1]
	s_cbranch_execz .LBB0_151
	global_load_dwordx4 v[136:139], v[150:151], off offset:80
	global_load_dwordx4 v[140:143], v[150:151], off offset:64
	s_waitcnt lgkmcnt(1)
	v_pk_mul_f32 v[132:133], v[154:155], v[132:133] op_sel_hi:[0,1]
	s_waitcnt lgkmcnt(0)
	v_pk_mul_f32 v[128:129], v[154:155], v[128:129] op_sel_hi:[0,1]
	v_pk_mul_f32 v[134:135], v[154:155], v[134:135] op_sel_hi:[0,1]
	v_pk_mul_f32 v[130:131], v[154:155], v[130:131] op_sel_hi:[0,1]
	s_waitcnt vmcnt(1)
	v_pk_mul_f32 v[130:131], v[130:131], v[138:139]
	s_waitcnt vmcnt(0)
	v_pk_mul_f32 v[134:135], v[134:135], v[142:143]
	v_pk_mul_f32 v[128:129], v[128:129], v[136:137]
	v_pk_mul_f32 v[132:133], v[132:133], v[140:141]

; DI unsigned pack2(float a, float b) { f32x2 v = {a, b}; bfx2 r = __builtin_convertvector(v, bfx2); return __builtin_bit_cast(unsigned, r); }
; DI float sigmoidf_(float x) { return 1.f / (1.f + __expf(-x)); }
; template <int MODE, bool BIG = false> DI void gemm_tile(const Params& p, int tm, int tn, int kv, char* smem) {
;     ...
;     for (int c8 = 0; c8 < 8; ++c8) {
;       float4 v0 = crow4[2 * c8], v1 = crow4[2 * c8 + 1];
;       float v[8] = {v0.x, v0.y, v0.z, v0.w, v1.x, v1.y, v1.z, v1.w};
;       if (g) {
; #pragma unroll
;         for (int e = 0; e < 8; ++e) v[e] = v[e] * sc * g[c8 * 8 + e];
;       } else if (region == 48) {
; #pragma unroll
;         for (int e = 0; e < 8; ++e) { int c = c8 * 8 + e; v[e] = c < 24 ? sigmoidf_(v[e] + p.gate_b[c]) : 0.f; }
;       }
;       *(uint4*)(proj + prow(m) + col0 + c8 * 8) = make_uint4(pack2(v[0], v[1]), pack2(v[2], v[3]), pack2(v[4], v[5]), pack2(v[6], v[7]));
.LBB0_155:
	s_or_b64 exec, exec, s[22:23]
	ds_read_b128 v[140:143], v159 offset:96
	ds_read_b128 v[136:139], v159 offset:112
	s_waitcnt lgkmcnt(3)
	v_cvt_pk_f16_f32 v132, v132, v133
	v_cvt_pk_f16_f32 v133, v134, v135
	s_waitcnt lgkmcnt(2)
	v_cvt_pk_f16_f32 v134, v128, v129
	v_cvt_pk_f16_f32 v135, v130, v131
	ds_write_b128 v159, v[132:135] offset:32
	s_and_saveexec_b64 s[0:1], s[10:11]
	s_xor_b64 s[0:1], exec, s[0:1]
	s_cbranch_execz .LBB0_157
	global_load_dwordx4 v[128:131], v[150:151], off offset:112
	global_load_dwordx4 v[132:135], v[150:151], off offset:96
	s_waitcnt lgkmcnt(1)
	v_pk_mul_f32 v[140:141], v[154:155], v[140:141] op_sel_hi:[0,1]
	s_waitcnt lgkmcnt(0)
	v_pk_mul_f32 v[136:137], v[154:155], v[136:137] op_sel_hi:[0,1]
	v_pk_mul_f32 v[142:143], v[154:155], v[142:143] op_sel_hi:[0,1]
	v_pk_mul_f32 v[138:139], v[154:155], v[138:139] op_sel_hi:[0,1]
	s_waitcnt vmcnt(1)
	v_pk_mul_f32 v[138:139], v[138:139], v[130:131]
	s_waitcnt vmcnt(0)
	v_pk_mul_f32 v[142:143], v[142:143], v[134:135]
	v_pk_mul_f32 v[136:137], v[136:137], v[128:129]
	v_pk_mul_f32 v[140:141], v[140:141], v[132:133]

; DI unsigned pack2(float a, float b) { f32x2 v = {a, b}; bfx2 r = __builtin_convertvector(v, bfx2); return __builtin_bit_cast(unsigned, r); }
; DI float sigmoidf_(float x) { return 1.f / (1.f + __expf(-x)); }
; template <int MODE, bool BIG = false> DI void gemm_tile(const Params& p, int tm, int tn, int kv, char* smem) {
;     ...
;     for (int c8 = 0; c8 < 8; ++c8) {
;       float4 v0 = crow4[2 * c8], v1 = crow4[2 * c8 + 1];
;       float v[8] = {v0.x, v0.y, v0.z, v0.w, v1.x, v1.y, v1.z, v1.w};
;       if (g) {
; #pragma unroll
;         for (int e = 0; e < 8; ++e) v[e] = v[e] * sc * g[c8 * 8 + e];
;       } else if (region == 48) {
; #pragma unroll
;         for (int e = 0; e < 8; ++e) { int c = c8 * 8 + e; v[e] = c < 24 ? sigmoidf_(v[e] + p.gate_b[c]) : 0.f; }
;       }
;       *(uint4*)(proj + prow(m) + col0 + c8 * 8) = make_uint4(pack2(v[0], v[1]), pack2(v[2], v[3]), pack2(v[4], v[5]), pack2(v[6], v[7]));
.LBB0_161:
	s_or_b64 exec, exec, s[0:1]
	ds_read_b128 v[144:147], v159 offset:128
	ds_read_b128 v[128:131], v159 offset:144
	s_waitcnt lgkmcnt(3)
	v_cvt_pk_f16_f32 v132, v140, v141
	v_cvt_pk_f16_f32 v133, v142, v143
	s_waitcnt lgkmcnt(2)
	v_cvt_pk_f16_f32 v134, v136, v137
	v_cvt_pk_f16_f32 v135, v138, v139
	ds_write_b128 v159, v[132:135] offset:48
	s_and_saveexec_b64 s[0:1], s[10:11]
	s_xor_b64 s[0:1], exec, s[0:1]
	s_cbranch_execz .LBB0_163
	global_load_dwordx4 v[132:135], v[150:151], off offset:144
	global_load_dwordx4 v[136:139], v[150:151], off offset:128
	s_waitcnt lgkmcnt(1)
	v_pk_mul_f32 v[140:141], v[154:155], v[144:145] op_sel_hi:[0,1]
	s_waitcnt lgkmcnt(0)
	v_pk_mul_f32 v[128:129], v[154:155], v[128:129] op_sel_hi:[0,1]
	v_pk_mul_f32 v[142:143], v[154:155], v[146:147] op_sel_hi:[0,1]
	v_pk_mul_f32 v[130:131], v[154:155], v[130:131] op_sel_hi:[0,1]
	s_waitcnt vmcnt(1)
	v_pk_mul_f32 v[130:131], v[130:131], v[134:135]
	s_waitcnt vmcnt(0)
	v_pk_mul_f32 v[146:147], v[142:143], v[138:139]
	v_pk_mul_f32 v[128:129], v[128:129], v[132:133]
	v_pk_mul_f32 v[144:145], v[140:141], v[136:137]

; DI unsigned pack2(float a, float b) { f32x2 v = {a, b}; bfx2 r = __builtin_convertvector(v, bfx2); return __builtin_bit_cast(unsigned, r); }
; DI float sigmoidf_(float x) { return 1.f / (1.f + __expf(-x)); }
; template <int MODE, bool BIG = false> DI void gemm_tile(const Params& p, int tm, int tn, int kv, char* smem) {
;     ...
;     for (int c8 = 0; c8 < 8; ++c8) {
;       float4 v0 = crow4[2 * c8], v1 = crow4[2 * c8 + 1];
;       float v[8] = {v0.x, v0.y, v0.z, v0.w, v1.x, v1.y, v1.z, v1.w};
;       if (g) {
; #pragma unroll
;         for (int e = 0; e < 8; ++e) v[e] = v[e] * sc * g[c8 * 8 + e];
;       } else if (region == 48) {
; #pragma unroll
;         for (int e = 0; e < 8; ++e) { int c = c8 * 8 + e; v[e] = c < 24 ? sigmoidf_(v[e] + p.gate_b[c]) : 0.f; }
;       }
;       *(uint4*)(proj + prow(m) + col0 + c8 * 8) = make_uint4(pack2(v[0], v[1]), pack2(v[2], v[3]), pack2(v[4], v[5]), pack2(v[6], v[7]));
.LBB0_167:
	s_or_b64 exec, exec, s[0:1]
	ds_read_b128 v[136:139], v159 offset:160
	ds_read_b128 v[132:135], v159 offset:176
	s_waitcnt lgkmcnt(3)
	v_cvt_pk_f16_f32 v140, v144, v145
	v_cvt_pk_f16_f32 v141, v146, v147
	s_waitcnt lgkmcnt(2)
	v_cvt_pk_f16_f32 v142, v128, v129
	v_cvt_pk_f16_f32 v143, v130, v131
	ds_write_b128 v159, v[140:143] offset:64
	s_and_saveexec_b64 s[0:1], s[10:11]
	s_xor_b64 s[0:1], exec, s[0:1]
	s_cbranch_execz .LBB0_169
	global_load_dwordx4 v[128:131], v[150:151], off offset:176
	global_load_dwordx4 v[140:143], v[150:151], off offset:160
	s_waitcnt lgkmcnt(1)
	v_pk_mul_f32 v[136:137], v[154:155], v[136:137] op_sel_hi:[0,1]
	s_waitcnt lgkmcnt(0)
	v_pk_mul_f32 v[132:133], v[154:155], v[132:133] op_sel_hi:[0,1]
	v_pk_mul_f32 v[138:139], v[154:155], v[138:139] op_sel_hi:[0,1]
	v_pk_mul_f32 v[134:135], v[154:155], v[134:135] op_sel_hi:[0,1]
	s_waitcnt vmcnt(1)
	v_pk_mul_f32 v[134:135], v[134:135], v[130:131]
	s_waitcnt vmcnt(0)
	v_pk_mul_f32 v[138:139], v[138:139], v[142:143]
	v_pk_mul_f32 v[132:133], v[132:133], v[128:129]
	v_pk_mul_f32 v[136:137], v[136:137], v[140:141]

; DI unsigned pack2(float a, float b) { f32x2 v = {a, b}; bfx2 r = __builtin_convertvector(v, bfx2); return __builtin_bit_cast(unsigned, r); }
; DI float sigmoidf_(float x) { return 1.f / (1.f + __expf(-x)); }
; template <int MODE, bool BIG = false> DI void gemm_tile(const Params& p, int tm, int tn, int kv, char* smem) {
;     ...
;     for (int c8 = 0; c8 < 8; ++c8) {
;       float4 v0 = crow4[2 * c8], v1 = crow4[2 * c8 + 1];
;       float v[8] = {v0.x, v0.y, v0.z, v0.w, v1.x, v1.y, v1.z, v1.w};
;       if (g) {
; #pragma unroll
;         for (int e = 0; e < 8; ++e) v[e] = v[e] * sc * g[c8 * 8 + e];
;       } else if (region == 48) {
; #pragma unroll
;         for (int e = 0; e < 8; ++e) { int c = c8 * 8 + e; v[e] = c < 24 ? sigmoidf_(v[e] + p.gate_b[c]) : 0.f; }
;       }
;       *(uint4*)(proj + prow(m) + col0 + c8 * 8) = make_uint4(pack2(v[0], v[1]), pack2(v[2], v[3]), pack2(v[4], v[5]), pack2(v[6], v[7]));
.LBB0_173:
	s_or_b64 exec, exec, s[0:1]
	ds_read_b128 v[140:143], v159 offset:192
	ds_read_b128 v[128:131], v159 offset:208
	s_waitcnt lgkmcnt(3)
	v_cvt_pk_f16_f32 v136, v136, v137
	v_cvt_pk_f16_f32 v137, v138, v139
	s_waitcnt lgkmcnt(2)
	v_cvt_pk_f16_f32 v138, v132, v133
	v_cvt_pk_f16_f32 v139, v134, v135
	ds_write_b128 v159, v[136:139] offset:80
	s_and_saveexec_b64 s[0:1], s[10:11]
	s_xor_b64 s[0:1], exec, s[0:1]
	s_cbranch_execz .LBB0_175
	global_load_dwordx4 v[132:135], v[150:151], off offset:208
	global_load_dwordx4 v[136:139], v[150:151], off offset:192
	s_waitcnt lgkmcnt(1)
	v_pk_mul_f32 v[140:141], v[154:155], v[140:141] op_sel_hi:[0,1]
	s_waitcnt lgkmcnt(0)
	v_pk_mul_f32 v[128:129], v[154:155], v[128:129] op_sel_hi:[0,1]
	v_pk_mul_f32 v[142:143], v[154:155], v[142:143] op_sel_hi:[0,1]
	v_pk_mul_f32 v[130:131], v[154:155], v[130:131] op_sel_hi:[0,1]
	s_waitcnt vmcnt(1)
	v_pk_mul_f32 v[130:131], v[130:131], v[134:135]
	s_waitcnt vmcnt(0)
	v_pk_mul_f32 v[142:143], v[142:143], v[138:139]
	v_pk_mul_f32 v[128:129], v[128:129], v[132:133]
	v_pk_mul_f32 v[140:141], v[140:141], v[136:137]

; DI unsigned pack2(float a, float b) { f32x2 v = {a, b}; bfx2 r = __builtin_convertvector(v, bfx2); return __builtin_bit_cast(unsigned, r); }
; DI float sigmoidf_(float x) { return 1.f / (1.f + __expf(-x)); }
; template <int MODE, bool BIG = false> DI void gemm_tile(const Params& p, int tm, int tn, int kv, char* smem) {
;     ...
;     for (int c8 = 0; c8 < 8; ++c8) {
;       float4 v0 = crow4[2 * c8], v1 = crow4[2 * c8 + 1];
;       float v[8] = {v0.x, v0.y, v0.z, v0.w, v1.x, v1.y, v1.z, v1.w};
;       if (g) {
; #pragma unroll
;         for (int e = 0; e < 8; ++e) v[e] = v[e] * sc * g[c8 * 8 + e];
;       } else if (region == 48) {
; #pragma unroll
;         for (int e = 0; e < 8; ++e) { int c = c8 * 8 + e; v[e] = c < 24 ? sigmoidf_(v[e] + p.gate_b[c]) : 0.f; }
;       }
;       *(uint4*)(proj + prow(m) + col0 + c8 * 8) = make_uint4(pack2(v[0], v[1]), pack2(v[2], v[3]), pack2(v[4], v[5]), pack2(v[6], v[7]));
.LBB0_179:
	s_or_b64 exec, exec, s[0:1]
	ds_read_b128 v[136:139], v159 offset:224
	ds_read_b128 v[132:135], v159 offset:240
	s_waitcnt lgkmcnt(3)
	v_cvt_pk_f16_f32 v140, v140, v141
	v_cvt_pk_f16_f32 v141, v142, v143
	s_waitcnt lgkmcnt(2)
	v_cvt_pk_f16_f32 v142, v128, v129
	v_cvt_pk_f16_f32 v143, v130, v131
	ds_write_b128 v159, v[140:143] offset:96
	s_and_saveexec_b64 s[0:1], s[10:11]
	s_xor_b64 s[0:1], exec, s[0:1]
	s_cbranch_execz .LBB0_181
	global_load_dwordx4 v[128:131], v[150:151], off offset:240
	global_load_dwordx4 v[140:143], v[150:151], off offset:224
	s_waitcnt lgkmcnt(1)
	v_pk_mul_f32 v[136:137], v[154:155], v[136:137] op_sel_hi:[0,1]
	s_waitcnt lgkmcnt(0)
	v_pk_mul_f32 v[132:133], v[154:155], v[132:133] op_sel_hi:[0,1]
	v_pk_mul_f32 v[138:139], v[154:155], v[138:139] op_sel_hi:[0,1]
	v_pk_mul_f32 v[134:135], v[154:155], v[134:135] op_sel_hi:[0,1]
	s_waitcnt vmcnt(1)
	v_pk_mul_f32 v[134:135], v[134:135], v[130:131]
	s_waitcnt vmcnt(0)
	v_pk_mul_f32 v[138:139], v[138:139], v[142:143]
	v_pk_mul_f32 v[132:133], v[132:133], v[128:129]
	v_pk_mul_f32 v[136:137], v[136:137], v[140:141]
